# fp8 gate-logit epilogue: all four bias loads issued together at the top (on top of v41)
# speedup vs baseline: 1.0164x; 1.0008x over previous
.LBB0_282:
	s_lshl_b32 s4, s50, 8
	v_mov_b32_e32 v12, v1
	v_mov_b32_e32 v13, v227
	s_or_b32 s4, s4, s38
	s_andn2_b64 vcc, exec, s[2:3]
	v_lshl_add_u32 v10, v13, 3, s4
	v_ashrrev_i32_e32 v11, 31, v10
	v_lshl_add_u64 v[2:3], v[10:11], 2, s[10:11]
	global_load_dwordx4 v[32:35], v[2:3], off
	global_load_dwordx4 v[36:39], v[2:3], off offset:16
	global_load_dwordx4 v[40:43], v[2:3], off offset:512
	global_load_dwordx4 v[44:47], v[2:3], off offset:528
	s_nop 0
	s_lshl_b32 s4, s49, 8
	v_and_b32_e32 v11, 1, v13
	s_add_i32 s4, s4, s37
	v_lshlrev_b32_e32 v13, 4, v11
	v_add3_u32 v14, s4, v12, v13
	v_lshlrev_b32_e32 v11, 3, v11
	v_sub_u32_e32 v12, v10, v11
	v_ashrrev_i32_e32 v13, 31, v12
	s_mov_b64 s[2:3], -1
	s_waitcnt vmcnt(3)
	v_pk_add_f32 v[18:19], v[222:223], v[32:33]
	s_waitcnt vmcnt(2)
	v_pk_add_f32 v[22:23], v[218:219], v[36:37]
	v_exp_f32_e32 v15, v18
	v_pk_add_f32 v[16:17], v[224:225], v[34:35]
	v_exp_f32_e32 v18, v19
	v_exp_f32_e32 v19, v22
	v_pk_add_f32 v[20:21], v[220:221], v[38:39]
	v_exp_f32_e32 v16, v16
	v_exp_f32_e32 v22, v23
	v_pk_add_f32 v[26:27], v[214:215], v[32:33]
	v_exp_f32_e32 v17, v17
	v_exp_f32_e32 v20, v20
	v_pk_add_f32 v[30:31], v[210:211], v[36:37]
	v_exp_f32_e32 v23, v26
	v_fmamk_f32 v15, v15, 0x3b808081, v251
	v_pk_add_f32 v[24:25], v[216:217], v[34:35]
	v_exp_f32_e32 v26, v27
	v_exp_f32_e32 v27, v30
	v_fmamk_f32 v18, v18, 0x3b808081, v251
	v_fmamk_f32 v19, v19, 0x3b808081, v251
	v_rcp_f32_e32 v15, v15
	v_pk_add_f32 v[28:29], v[212:213], v[38:39]
	v_exp_f32_e32 v21, v21
	v_exp_f32_e32 v24, v24
	v_exp_f32_e32 v30, v31
	v_fmamk_f32 v16, v16, 0x3b808081, v251
	v_fmamk_f32 v22, v22, 0x3b808081, v251
	v_rcp_f32_e32 v18, v18
	v_rcp_f32_e32 v19, v19
	v_exp_f32_e32 v28, v28
	v_fmamk_f32 v17, v17, 0x3b808081, v251
	v_fmamk_f32 v20, v20, 0x3b808081, v251
	v_rcp_f32_e32 v16, v16
	v_rcp_f32_e32 v22, v22
	v_exp_f32_e32 v29, v29
	v_fmamk_f32 v23, v23, 0x3b808081, v251
	v_rcp_f32_e32 v17, v17
	v_rcp_f32_e32 v20, v20
	v_fmamk_f32 v26, v26, 0x3b808081, v251
	v_fmamk_f32 v27, v27, 0x3b808081, v251
	v_rcp_f32_e32 v23, v23
	v_rndne_f32_e32 v15, v15
	v_exp_f32_e32 v25, v25
	v_fmamk_f32 v21, v21, 0x3b808081, v251
	v_fmamk_f32 v24, v24, 0x3b808081, v251
	v_fmamk_f32 v30, v30, 0x3b808081, v251
	v_rcp_f32_e32 v26, v26
	v_rcp_f32_e32 v27, v27
	v_rndne_f32_e32 v18, v18
	v_rndne_f32_e32 v19, v19
	v_cvt_pk_u8_f32 v15, v15, 0, 0
	v_fmamk_f32 v28, v28, 0x3b808081, v251
	v_rcp_f32_e32 v21, v21
	v_rcp_f32_e32 v24, v24
	v_rcp_f32_e32 v30, v30
	v_rndne_f32_e32 v16, v16
	v_rndne_f32_e32 v22, v22
	v_cvt_pk_u8_f32 v19, v19, 0, 0
	v_cvt_pk_u8_f32 v15, v18, 1, v15
	v_fmamk_f32 v29, v29, 0x3b808081, v251
	v_rcp_f32_e32 v28, v28
	v_rndne_f32_e32 v17, v17
	v_rndne_f32_e32 v20, v20
	v_cvt_pk_u8_f32 v18, v22, 1, v19
	v_cvt_pk_u8_f32 v15, v16, 2, v15
	v_rndne_f32_e32 v23, v23
	v_cvt_pk_u8_f32 v16, v20, 2, v18
	v_cvt_pk_u8_f32 v18, v17, 3, v15
	v_rcp_f32_e32 v15, v29
	v_fmamk_f32 v25, v25, 0x3b808081, v251
	v_rndne_f32_e32 v26, v26
	v_rndne_f32_e32 v27, v27
	v_cvt_pk_u8_f32 v23, v23, 0, 0
	v_rcp_f32_e32 v25, v25
	v_rndne_f32_e32 v21, v21
	v_rndne_f32_e32 v24, v24
	v_rndne_f32_e32 v30, v30
	v_cvt_pk_u8_f32 v27, v27, 0, 0
	v_cvt_pk_u8_f32 v19, v26, 1, v23
	v_cvt_pk_u8_f32 v20, v24, 2, v19
	v_cvt_pk_u8_f32 v19, v21, 3, v16
	v_cvt_pk_u8_f32 v16, v30, 1, v27
	v_rndne_f32_e32 v17, v28
	v_cvt_pk_u8_f32 v16, v17, 2, v16
	v_rndne_f32_e32 v15, v15
	v_cvt_pk_u8_f32 v21, v15, 3, v16
	v_ashrrev_i32_e32 v15, 31, v14
	v_rndne_f32_e32 v25, v25
	v_lshlrev_b64 v[16:17], 10, v[14:15]
	v_cvt_pk_u8_f32 v20, v25, 3, v20
	v_lshl_add_u64 v[16:17], s[74:75], 0, v[16:17]
	s_nop 0
	v_permlane16_swap_b32_e32 v18, v20
	v_permlane16_swap_b32_e32 v19, v21
	v_lshl_add_u64 v[22:23], v[16:17], 0, v[12:13]
	global_store_dwordx4 v[22:23], v[18:21], off
	v_pk_add_f32 v[22:23], v[204:205], v[38:39]
	v_pk_add_f32 v[24:25], v[196:197], v[38:39]
	v_pk_add_f32 v[18:19], v[206:207], v[32:33]
	v_pk_add_f32 v[20:21], v[208:209], v[34:35]
	v_exp_f32_e32 v15, v18
	v_exp_f32_e32 v18, v19
	v_exp_f32_e32 v19, v20
	v_exp_f32_e32 v20, v21
	v_fmamk_f32 v15, v15, 0x3b808081, v251
	v_rcp_f32_e32 v15, v15
	v_fmamk_f32 v18, v18, 0x3b808081, v251
	v_rcp_f32_e32 v18, v18
	v_fmamk_f32 v19, v19, 0x3b808081, v251
	v_rcp_f32_e32 v19, v19
	v_fmamk_f32 v20, v20, 0x3b808081, v251
	v_rcp_f32_e32 v20, v20
	v_rndne_f32_e32 v15, v15
	v_cvt_pk_u8_f32 v15, v15, 0, 0
	v_rndne_f32_e32 v18, v18
	v_cvt_pk_u8_f32 v15, v18, 1, v15
	v_rndne_f32_e32 v18, v19
	v_cvt_pk_u8_f32 v15, v18, 2, v15
	v_rndne_f32_e32 v18, v20
	v_cvt_pk_u8_f32 v20, v18, 3, v15
	v_pk_add_f32 v[18:19], v[202:203], v[36:37]
	v_exp_f32_e32 v21, v23
	v_exp_f32_e32 v15, v18
	v_exp_f32_e32 v18, v19
	v_exp_f32_e32 v19, v22
	v_fmamk_f32 v21, v21, 0x3b808081, v251
	v_fmamk_f32 v15, v15, 0x3b808081, v251
	v_rcp_f32_e32 v15, v15
	v_fmamk_f32 v18, v18, 0x3b808081, v251
	v_rcp_f32_e32 v18, v18
	v_fmamk_f32 v19, v19, 0x3b808081, v251
	v_rcp_f32_e32 v19, v19
	v_rcp_f32_e32 v21, v21
	v_rndne_f32_e32 v15, v15
	v_cvt_pk_u8_f32 v15, v15, 0, 0
	v_rndne_f32_e32 v18, v18
	v_cvt_pk_u8_f32 v15, v18, 1, v15
	v_rndne_f32_e32 v18, v19
	v_cvt_pk_u8_f32 v15, v18, 2, v15
	v_rndne_f32_e32 v18, v21
	v_cvt_pk_u8_f32 v21, v18, 3, v15
	v_pk_add_f32 v[18:19], v[198:199], v[32:33]
	v_pk_add_f32 v[22:23], v[200:201], v[34:35]
	v_exp_f32_e32 v15, v18
	v_exp_f32_e32 v18, v19
	v_exp_f32_e32 v19, v22
	v_exp_f32_e32 v22, v23
	v_fmamk_f32 v15, v15, 0x3b808081, v251
	v_rcp_f32_e32 v15, v15
	v_fmamk_f32 v18, v18, 0x3b808081, v251
	v_rcp_f32_e32 v18, v18
	v_fmamk_f32 v19, v19, 0x3b808081, v251
	v_rcp_f32_e32 v19, v19
	v_fmamk_f32 v22, v22, 0x3b808081, v251
	v_rcp_f32_e32 v22, v22
	v_rndne_f32_e32 v15, v15
	v_cvt_pk_u8_f32 v15, v15, 0, 0
	v_rndne_f32_e32 v18, v18
	v_cvt_pk_u8_f32 v15, v18, 1, v15
	v_rndne_f32_e32 v18, v19
	v_cvt_pk_u8_f32 v15, v18, 2, v15
	v_rndne_f32_e32 v18, v22
	v_cvt_pk_u8_f32 v22, v18, 3, v15
	v_pk_add_f32 v[18:19], v[194:195], v[36:37]
	v_exp_f32_e32 v23, v25
	v_exp_f32_e32 v15, v18
	v_exp_f32_e32 v18, v19
	v_exp_f32_e32 v19, v24
	v_fmamk_f32 v23, v23, 0x3b808081, v251
	v_fmamk_f32 v15, v15, 0x3b808081, v251
	v_rcp_f32_e32 v15, v15
	v_fmamk_f32 v18, v18, 0x3b808081, v251
	v_rcp_f32_e32 v18, v18
	v_fmamk_f32 v19, v19, 0x3b808081, v251
	v_rcp_f32_e32 v19, v19
	v_rcp_f32_e32 v23, v23
	v_rndne_f32_e32 v15, v15
	v_cvt_pk_u8_f32 v15, v15, 0, 0
	v_rndne_f32_e32 v18, v18
	v_cvt_pk_u8_f32 v15, v18, 1, v15
	v_rndne_f32_e32 v18, v19
	v_cvt_pk_u8_f32 v15, v18, 2, v15
	v_rndne_f32_e32 v18, v23
	v_cvt_pk_u8_f32 v23, v18, 3, v15
	v_add_u32_e32 v18, 32, v14
	v_ashrrev_i32_e32 v19, 31, v18
	v_lshlrev_b64 v[18:19], 10, v[18:19]
	v_lshl_add_u64 v[18:19], s[74:75], 0, v[18:19]
	v_permlane16_swap_b32_e32 v20, v22
	v_permlane16_swap_b32_e32 v21, v23
	v_lshl_add_u64 v[24:25], v[18:19], 0, v[12:13]
	global_store_dwordx4 v[24:25], v[20:23], off
	v_pk_add_f32 v[24:25], v[192:193], v[34:35]
	v_pk_add_f32 v[26:27], v[188:189], v[38:39]
	v_pk_add_f32 v[22:23], v[190:191], v[32:33]
	v_pk_add_f32 v[28:29], v[180:181], v[38:39]
	v_exp_f32_e32 v15, v22
	v_exp_f32_e32 v21, v23
	v_exp_f32_e32 v22, v24
	v_exp_f32_e32 v23, v25
	v_fmamk_f32 v15, v15, 0x3b808081, v251
	v_rcp_f32_e32 v15, v15
	v_fmamk_f32 v21, v21, 0x3b808081, v251
	v_rcp_f32_e32 v21, v21
	v_fmamk_f32 v22, v22, 0x3b808081, v251
	v_rcp_f32_e32 v22, v22
	v_fmamk_f32 v23, v23, 0x3b808081, v251
	v_rcp_f32_e32 v23, v23
	v_rndne_f32_e32 v15, v15
	v_cvt_pk_u8_f32 v15, v15, 0, 0
	v_rndne_f32_e32 v21, v21
	v_cvt_pk_u8_f32 v15, v21, 1, v15
	v_rndne_f32_e32 v21, v22
	v_cvt_pk_u8_f32 v15, v21, 2, v15
	v_rndne_f32_e32 v21, v23
	v_pk_add_f32 v[24:25], v[186:187], v[36:37]
	v_cvt_pk_u8_f32 v22, v21, 3, v15
	v_exp_f32_e32 v15, v24
	v_exp_f32_e32 v21, v25
	v_exp_f32_e32 v23, v26
	v_exp_f32_e32 v24, v27
	v_fmamk_f32 v15, v15, 0x3b808081, v251
	v_rcp_f32_e32 v15, v15
	v_fmamk_f32 v21, v21, 0x3b808081, v251
	v_rcp_f32_e32 v21, v21
	v_fmamk_f32 v23, v23, 0x3b808081, v251
	v_rcp_f32_e32 v23, v23
	v_fmamk_f32 v24, v24, 0x3b808081, v251
	v_rcp_f32_e32 v24, v24
	v_rndne_f32_e32 v15, v15
	v_cvt_pk_u8_f32 v15, v15, 0, 0
	v_rndne_f32_e32 v21, v21
	v_cvt_pk_u8_f32 v15, v21, 1, v15
	v_rndne_f32_e32 v21, v23
	v_cvt_pk_u8_f32 v15, v21, 2, v15
	v_rndne_f32_e32 v21, v24
	v_pk_add_f32 v[24:25], v[182:183], v[32:33]
	v_cvt_pk_u8_f32 v23, v21, 3, v15
	v_exp_f32_e32 v15, v24
	v_pk_add_f32 v[26:27], v[184:185], v[34:35]
	v_exp_f32_e32 v21, v25
	v_exp_f32_e32 v24, v26
	v_exp_f32_e32 v25, v27
	v_fmamk_f32 v15, v15, 0x3b808081, v251
	v_rcp_f32_e32 v15, v15
	v_fmamk_f32 v21, v21, 0x3b808081, v251
	v_rcp_f32_e32 v21, v21
	v_fmamk_f32 v24, v24, 0x3b808081, v251
	v_rcp_f32_e32 v24, v24
	v_fmamk_f32 v25, v25, 0x3b808081, v251
	v_rcp_f32_e32 v25, v25
	v_rndne_f32_e32 v15, v15
	v_cvt_pk_u8_f32 v15, v15, 0, 0
	v_rndne_f32_e32 v21, v21
	v_cvt_pk_u8_f32 v15, v21, 1, v15
	v_rndne_f32_e32 v21, v24
	v_cvt_pk_u8_f32 v15, v21, 2, v15
	v_rndne_f32_e32 v21, v25
	v_pk_add_f32 v[26:27], v[178:179], v[36:37]
	v_cvt_pk_u8_f32 v24, v21, 3, v15
	v_exp_f32_e32 v15, v26
	v_exp_f32_e32 v21, v27
	v_exp_f32_e32 v25, v28
	v_exp_f32_e32 v26, v29
	v_fmamk_f32 v15, v15, 0x3b808081, v251
	v_rcp_f32_e32 v15, v15
	v_fmamk_f32 v21, v21, 0x3b808081, v251
	v_rcp_f32_e32 v21, v21
	v_fmamk_f32 v25, v25, 0x3b808081, v251
	v_rcp_f32_e32 v25, v25
	v_fmamk_f32 v26, v26, 0x3b808081, v251
	v_rcp_f32_e32 v26, v26
	v_rndne_f32_e32 v15, v15
	v_cvt_pk_u8_f32 v15, v15, 0, 0
	v_rndne_f32_e32 v21, v21
	v_cvt_pk_u8_f32 v15, v21, 1, v15
	v_rndne_f32_e32 v21, v25
	v_add_u32_e32 v20, 0x80, v14
	v_cvt_pk_u8_f32 v15, v21, 2, v15
	v_rndne_f32_e32 v21, v26
	v_cvt_pk_u8_f32 v25, v21, 3, v15
	v_ashrrev_i32_e32 v21, 31, v20
	v_lshlrev_b64 v[20:21], 10, v[20:21]
	v_lshl_add_u64 v[20:21], s[74:75], 0, v[20:21]
	v_permlane16_swap_b32_e32 v22, v24
	v_permlane16_swap_b32_e32 v23, v25
	v_lshl_add_u64 v[26:27], v[20:21], 0, v[12:13]
	global_store_dwordx4 v[26:27], v[22:25], off
	v_pk_add_f32 v[26:27], v[172:173], v[38:39]
	v_pk_add_f32 v[4:5], v[160:161], v[38:39]
	v_pk_add_f32 v[22:23], v[174:175], v[32:33]
	v_pk_add_f32 v[24:25], v[176:177], v[34:35]
	v_exp_f32_e32 v15, v22
	v_exp_f32_e32 v22, v23
	v_exp_f32_e32 v23, v24
	v_exp_f32_e32 v24, v25
	v_fmamk_f32 v15, v15, 0x3b808081, v251
	v_rcp_f32_e32 v15, v15
	v_fmamk_f32 v22, v22, 0x3b808081, v251
	v_rcp_f32_e32 v22, v22
	v_fmamk_f32 v23, v23, 0x3b808081, v251
	v_rcp_f32_e32 v23, v23
	v_fmamk_f32 v24, v24, 0x3b808081, v251
	v_rcp_f32_e32 v24, v24
	v_rndne_f32_e32 v15, v15
	v_cvt_pk_u8_f32 v15, v15, 0, 0
	v_rndne_f32_e32 v22, v22
	v_cvt_pk_u8_f32 v15, v22, 1, v15
	v_rndne_f32_e32 v22, v23
	v_cvt_pk_u8_f32 v15, v22, 2, v15
	v_rndne_f32_e32 v22, v24
	v_pk_add_f32 v[24:25], v[170:171], v[36:37]
	v_pk_add_f32 v[2:3], v[158:159], v[36:37]
	v_cvt_pk_u8_f32 v22, v22, 3, v15
	v_exp_f32_e32 v2, v2
	v_exp_f32_e32 v15, v24
	v_exp_f32_e32 v3, v3
	v_exp_f32_e32 v23, v25
	v_exp_f32_e32 v4, v4
	v_exp_f32_e32 v24, v26
	v_pk_add_f32 v[6:7], v[162:163], v[32:33]
	v_exp_f32_e32 v5, v5
	v_exp_f32_e32 v25, v27
	v_exp_f32_e32 v6, v6
	v_fmamk_f32 v2, v2, 0x3b808081, v251
	v_fmamk_f32 v15, v15, 0x3b808081, v251
	v_pk_add_f32 v[8:9], v[164:165], v[34:35]
	v_exp_f32_e32 v7, v7
	v_rcp_f32_e32 v2, v2
	v_fmamk_f32 v3, v3, 0x3b808081, v251
	v_rcp_f32_e32 v15, v15
	v_fmamk_f32 v23, v23, 0x3b808081, v251
	v_exp_f32_e32 v8, v8
	v_rcp_f32_e32 v3, v3
	v_fmamk_f32 v4, v4, 0x3b808081, v251
	v_rcp_f32_e32 v23, v23
	v_fmamk_f32 v24, v24, 0x3b808081, v251
	v_exp_f32_e32 v9, v9
	v_rcp_f32_e32 v4, v4
	v_fmamk_f32 v5, v5, 0x3b808081, v251
	v_rcp_f32_e32 v24, v24
	v_fmamk_f32 v25, v25, 0x3b808081, v251
	v_fmamk_f32 v6, v6, 0x3b808081, v251
	v_rcp_f32_e32 v5, v5
	v_rcp_f32_e32 v25, v25
	v_rcp_f32_e32 v6, v6
	v_fmamk_f32 v7, v7, 0x3b808081, v251
	v_rndne_f32_e32 v2, v2
	v_rndne_f32_e32 v15, v15
	v_rcp_f32_e32 v7, v7
	v_fmamk_f32 v8, v8, 0x3b808081, v251
	v_cvt_pk_u8_f32 v2, v2, 0, 0
	v_rndne_f32_e32 v3, v3
	v_cvt_pk_u8_f32 v15, v15, 0, 0
	v_rndne_f32_e32 v23, v23
	v_rcp_f32_e32 v8, v8
	v_fmamk_f32 v9, v9, 0x3b808081, v251
	v_cvt_pk_u8_f32 v2, v3, 1, v2
	v_rndne_f32_e32 v3, v4
	v_cvt_pk_u8_f32 v15, v23, 1, v15
	v_rndne_f32_e32 v23, v24
	v_rcp_f32_e32 v9, v9
	v_cvt_pk_u8_f32 v2, v3, 2, v2
	v_rndne_f32_e32 v3, v5
	v_cvt_pk_u8_f32 v15, v23, 2, v15
	v_rndne_f32_e32 v23, v25
	v_rndne_f32_e32 v6, v6
	v_cvt_pk_u8_f32 v25, v3, 3, v2
	v_add_u32_e32 v2, 0xa0, v14
	v_cvt_pk_u8_f32 v6, v6, 0, 0
	v_rndne_f32_e32 v7, v7
	v_ashrrev_i32_e32 v3, 31, v2
	v_cvt_pk_u8_f32 v6, v7, 1, v6
	v_rndne_f32_e32 v7, v8
	v_lshlrev_b64 v[2:3], 10, v[2:3]
	v_cvt_pk_u8_f32 v23, v23, 3, v15
	v_cvt_pk_u8_f32 v6, v7, 2, v6
	v_rndne_f32_e32 v7, v9
	v_lshl_add_u64 v[14:15], s[74:75], 0, v[2:3]
	v_cvt_pk_u8_f32 v24, v7, 3, v6
	v_lshl_add_u64 v[2:3], v[14:15], 0, v[12:13]
	v_add_u32_e32 v12, 0x80, v10
	v_permlane16_swap_b32_e32 v22, v24
	v_permlane16_swap_b32_e32 v23, v25
	v_ashrrev_i32_e32 v13, 31, v12
	global_store_dwordx4 v[2:3], v[22:25], off
	v_lshl_add_u64 v[2:3], v[12:13], 2, s[10:11]
	s_nop 0
	v_sub_u32_e32 v10, v12, v11
	v_ashrrev_i32_e32 v11, 31, v10
	s_waitcnt vmcnt(5)
	v_pk_add_f32 v[12:13], v[166:167], v[40:41]
	s_nop 0
	v_exp_f32_e32 v12, v12
	v_pk_add_f32 v[22:23], v[168:169], v[42:43]
	v_exp_f32_e32 v13, v13
	v_exp_f32_e32 v22, v22
	v_exp_f32_e32 v23, v23
	v_fmamk_f32 v12, v12, 0x3b808081, v251
	v_rcp_f32_e32 v12, v12
	v_fmamk_f32 v13, v13, 0x3b808081, v251
	v_rcp_f32_e32 v13, v13
	v_fmamk_f32 v22, v22, 0x3b808081, v251
	v_rcp_f32_e32 v22, v22
	v_fmamk_f32 v23, v23, 0x3b808081, v251
	v_rcp_f32_e32 v23, v23
	v_rndne_f32_e32 v12, v12
	v_cvt_pk_u8_f32 v12, v12, 0, 0
	v_rndne_f32_e32 v13, v13
	v_cvt_pk_u8_f32 v12, v13, 1, v12
	v_rndne_f32_e32 v13, v22
	v_cvt_pk_u8_f32 v12, v13, 2, v12
	v_rndne_f32_e32 v13, v23
	v_cvt_pk_u8_f32 v22, v13, 3, v12
	s_waitcnt vmcnt(4)
	v_pk_add_f32 v[12:13], v[154:155], v[44:45]
	v_pk_add_f32 v[24:25], v[156:157], v[46:47]
	v_exp_f32_e32 v12, v12
	v_exp_f32_e32 v13, v13
	v_exp_f32_e32 v23, v24
	v_exp_f32_e32 v24, v25
	v_fmamk_f32 v12, v12, 0x3b808081, v251
	v_rcp_f32_e32 v12, v12
	v_fmamk_f32 v13, v13, 0x3b808081, v251
	v_rcp_f32_e32 v13, v13
	v_fmamk_f32 v23, v23, 0x3b808081, v251
	v_rcp_f32_e32 v23, v23
	v_fmamk_f32 v24, v24, 0x3b808081, v251
	v_rcp_f32_e32 v24, v24
	v_rndne_f32_e32 v12, v12
	v_cvt_pk_u8_f32 v12, v12, 0, 0
	v_rndne_f32_e32 v13, v13
	v_cvt_pk_u8_f32 v12, v13, 1, v12
	v_rndne_f32_e32 v13, v23
	v_cvt_pk_u8_f32 v12, v13, 2, v12
	v_rndne_f32_e32 v13, v24
	v_cvt_pk_u8_f32 v23, v13, 3, v12
	v_pk_add_f32 v[12:13], v[150:151], v[40:41]
	v_pk_add_f32 v[24:25], v[152:153], v[42:43]
	v_exp_f32_e32 v12, v12
	v_exp_f32_e32 v13, v13
	v_exp_f32_e32 v24, v24
	v_exp_f32_e32 v25, v25
	v_fmamk_f32 v12, v12, 0x3b808081, v251
	v_rcp_f32_e32 v12, v12
	v_fmamk_f32 v13, v13, 0x3b808081, v251
	v_rcp_f32_e32 v13, v13
	v_fmamk_f32 v24, v24, 0x3b808081, v251
	v_rcp_f32_e32 v24, v24
	v_fmamk_f32 v25, v25, 0x3b808081, v251
	v_rcp_f32_e32 v25, v25
	v_rndne_f32_e32 v12, v12
	v_cvt_pk_u8_f32 v12, v12, 0, 0
	v_rndne_f32_e32 v13, v13
	v_cvt_pk_u8_f32 v12, v13, 1, v12
	v_rndne_f32_e32 v13, v24
	v_cvt_pk_u8_f32 v12, v13, 2, v12
	v_rndne_f32_e32 v13, v25
	v_cvt_pk_u8_f32 v24, v13, 3, v12
	v_pk_add_f32 v[12:13], v[146:147], v[44:45]
	v_pk_add_f32 v[26:27], v[148:149], v[46:47]
	v_exp_f32_e32 v12, v12
	v_exp_f32_e32 v13, v13
	v_exp_f32_e32 v25, v26
	v_exp_f32_e32 v26, v27
	v_fmamk_f32 v12, v12, 0x3b808081, v251
	v_rcp_f32_e32 v12, v12
	v_fmamk_f32 v13, v13, 0x3b808081, v251
	v_rcp_f32_e32 v13, v13
	v_fmamk_f32 v25, v25, 0x3b808081, v251
	v_rcp_f32_e32 v25, v25
	v_fmamk_f32 v26, v26, 0x3b808081, v251
	v_rcp_f32_e32 v26, v26
	v_rndne_f32_e32 v12, v12
	v_cvt_pk_u8_f32 v12, v12, 0, 0
	v_rndne_f32_e32 v13, v13
	v_cvt_pk_u8_f32 v12, v13, 1, v12
	v_rndne_f32_e32 v13, v25
	v_cvt_pk_u8_f32 v12, v13, 2, v12
	v_rndne_f32_e32 v13, v26
	v_cvt_pk_u8_f32 v25, v13, 3, v12
	v_permlane16_swap_b32_e32 v22, v24
	s_nop 0
	v_permlane16_swap_b32_e32 v23, v25
	v_lshl_add_u64 v[12:13], v[16:17], 0, v[10:11]
	global_store_dwordx4 v[12:13], v[22:25], off
	v_pk_add_f32 v[12:13], v[142:143], v[40:41]
	v_pk_add_f32 v[16:17], v[144:145], v[42:43]
	v_exp_f32_e32 v12, v12
	v_exp_f32_e32 v13, v13
	v_exp_f32_e32 v16, v16
	v_exp_f32_e32 v17, v17
	v_fmamk_f32 v12, v12, 0x3b808081, v251
	v_rcp_f32_e32 v12, v12
	v_fmamk_f32 v13, v13, 0x3b808081, v251
	v_rcp_f32_e32 v13, v13
	v_fmamk_f32 v16, v16, 0x3b808081, v251
	v_rcp_f32_e32 v16, v16
	v_fmamk_f32 v17, v17, 0x3b808081, v251
	v_rcp_f32_e32 v17, v17
	v_rndne_f32_e32 v12, v12
	v_cvt_pk_u8_f32 v12, v12, 0, 0
	v_rndne_f32_e32 v13, v13
	v_cvt_pk_u8_f32 v12, v13, 1, v12
	v_rndne_f32_e32 v13, v16
	v_cvt_pk_u8_f32 v12, v13, 2, v12
	v_rndne_f32_e32 v13, v17
	v_cvt_pk_u8_f32 v22, v13, 3, v12
	v_pk_add_f32 v[12:13], v[138:139], v[44:45]
	v_pk_add_f32 v[16:17], v[140:141], v[46:47]
	v_exp_f32_e32 v12, v12
	v_exp_f32_e32 v13, v13
	v_exp_f32_e32 v16, v16
	v_exp_f32_e32 v17, v17
	v_fmamk_f32 v12, v12, 0x3b808081, v251
	v_rcp_f32_e32 v12, v12
	v_fmamk_f32 v13, v13, 0x3b808081, v251
	v_rcp_f32_e32 v13, v13
	v_fmamk_f32 v16, v16, 0x3b808081, v251
	v_rcp_f32_e32 v16, v16
	v_fmamk_f32 v17, v17, 0x3b808081, v251
	v_rcp_f32_e32 v17, v17
	v_rndne_f32_e32 v12, v12
	v_cvt_pk_u8_f32 v12, v12, 0, 0
	v_rndne_f32_e32 v13, v13
	v_cvt_pk_u8_f32 v12, v13, 1, v12
	v_rndne_f32_e32 v13, v16
	v_cvt_pk_u8_f32 v12, v13, 2, v12
	v_rndne_f32_e32 v13, v17
	v_cvt_pk_u8_f32 v23, v13, 3, v12
	v_pk_add_f32 v[12:13], v[134:135], v[40:41]
	v_pk_add_f32 v[16:17], v[136:137], v[42:43]
	v_exp_f32_e32 v12, v12
	v_exp_f32_e32 v13, v13
	v_exp_f32_e32 v16, v16
	v_exp_f32_e32 v17, v17
	v_fmamk_f32 v12, v12, 0x3b808081, v251
	v_rcp_f32_e32 v12, v12
	v_fmamk_f32 v13, v13, 0x3b808081, v251
	v_rcp_f32_e32 v13, v13
	v_fmamk_f32 v16, v16, 0x3b808081, v251
	v_rcp_f32_e32 v16, v16
	v_fmamk_f32 v17, v17, 0x3b808081, v251
	v_rcp_f32_e32 v17, v17
	v_rndne_f32_e32 v12, v12
	v_cvt_pk_u8_f32 v12, v12, 0, 0
	v_rndne_f32_e32 v13, v13
	v_cvt_pk_u8_f32 v12, v13, 1, v12
	v_rndne_f32_e32 v13, v16
	v_cvt_pk_u8_f32 v12, v13, 2, v12
	v_rndne_f32_e32 v13, v17
	v_cvt_pk_u8_f32 v24, v13, 3, v12
	v_pk_add_f32 v[12:13], v[130:131], v[44:45]
	v_pk_add_f32 v[16:17], v[132:133], v[46:47]
	v_exp_f32_e32 v12, v12
	v_exp_f32_e32 v13, v13
	v_exp_f32_e32 v16, v16
	v_exp_f32_e32 v17, v17
	v_fmamk_f32 v12, v12, 0x3b808081, v251
	v_rcp_f32_e32 v12, v12
	v_fmamk_f32 v13, v13, 0x3b808081, v251
	v_rcp_f32_e32 v13, v13
	v_fmamk_f32 v16, v16, 0x3b808081, v251
	v_rcp_f32_e32 v16, v16
	v_fmamk_f32 v17, v17, 0x3b808081, v251
	v_rcp_f32_e32 v17, v17
	v_rndne_f32_e32 v12, v12
	v_cvt_pk_u8_f32 v12, v12, 0, 0
	v_rndne_f32_e32 v13, v13
	v_cvt_pk_u8_f32 v12, v13, 1, v12
	v_rndne_f32_e32 v13, v16
	v_cvt_pk_u8_f32 v12, v13, 2, v12
	v_rndne_f32_e32 v13, v17
	v_cvt_pk_u8_f32 v25, v13, 3, v12
	v_permlane16_swap_b32_e32 v22, v24
	s_nop 0
	v_permlane16_swap_b32_e32 v23, v25
	v_lshl_add_u64 v[12:13], v[18:19], 0, v[10:11]
	global_store_dwordx4 v[12:13], v[22:25], off
	v_pk_add_f32 v[12:13], v[126:127], v[40:41]
	v_pk_add_f32 v[16:17], v[128:129], v[42:43]
	v_exp_f32_e32 v12, v12
	v_exp_f32_e32 v13, v13
	v_exp_f32_e32 v16, v16
	v_exp_f32_e32 v17, v17
	v_fmamk_f32 v12, v12, 0x3b808081, v251
	v_rcp_f32_e32 v12, v12
	v_fmamk_f32 v13, v13, 0x3b808081, v251
	v_rcp_f32_e32 v13, v13
	v_fmamk_f32 v16, v16, 0x3b808081, v251
	v_rcp_f32_e32 v16, v16
	v_fmamk_f32 v17, v17, 0x3b808081, v251
	v_rcp_f32_e32 v17, v17
	v_rndne_f32_e32 v12, v12
	v_cvt_pk_u8_f32 v12, v12, 0, 0
	v_rndne_f32_e32 v13, v13
	v_cvt_pk_u8_f32 v12, v13, 1, v12
	v_rndne_f32_e32 v13, v16
	v_cvt_pk_u8_f32 v12, v13, 2, v12
	v_rndne_f32_e32 v13, v17
	v_cvt_pk_u8_f32 v16, v13, 3, v12
	v_pk_add_f32 v[12:13], v[122:123], v[44:45]
	v_pk_add_f32 v[18:19], v[124:125], v[46:47]
	v_exp_f32_e32 v12, v12
	v_exp_f32_e32 v13, v13
	v_exp_f32_e32 v17, v18
	v_exp_f32_e32 v18, v19
	v_fmamk_f32 v12, v12, 0x3b808081, v251
	v_rcp_f32_e32 v12, v12
	v_fmamk_f32 v13, v13, 0x3b808081, v251
	v_rcp_f32_e32 v13, v13
	v_fmamk_f32 v17, v17, 0x3b808081, v251
	v_rcp_f32_e32 v17, v17
	v_fmamk_f32 v18, v18, 0x3b808081, v251
	v_rcp_f32_e32 v18, v18
	v_rndne_f32_e32 v12, v12
	v_cvt_pk_u8_f32 v12, v12, 0, 0
	v_rndne_f32_e32 v13, v13
	v_cvt_pk_u8_f32 v12, v13, 1, v12
	v_rndne_f32_e32 v13, v17
	v_cvt_pk_u8_f32 v12, v13, 2, v12
	v_rndne_f32_e32 v13, v18
	v_cvt_pk_u8_f32 v17, v13, 3, v12
	v_pk_add_f32 v[12:13], v[118:119], v[40:41]
	v_pk_add_f32 v[18:19], v[120:121], v[42:43]
	v_exp_f32_e32 v12, v12
	v_exp_f32_e32 v13, v13
	v_exp_f32_e32 v18, v18
	v_exp_f32_e32 v19, v19
	v_fmamk_f32 v12, v12, 0x3b808081, v251
	v_rcp_f32_e32 v12, v12
	v_fmamk_f32 v13, v13, 0x3b808081, v251
	v_rcp_f32_e32 v13, v13
	v_fmamk_f32 v18, v18, 0x3b808081, v251
	v_rcp_f32_e32 v18, v18
	v_fmamk_f32 v19, v19, 0x3b808081, v251
	v_rcp_f32_e32 v19, v19
	v_rndne_f32_e32 v12, v12
	v_cvt_pk_u8_f32 v12, v12, 0, 0
	v_rndne_f32_e32 v13, v13
	v_cvt_pk_u8_f32 v12, v13, 1, v12
	v_rndne_f32_e32 v13, v18
	v_cvt_pk_u8_f32 v12, v13, 2, v12
	v_rndne_f32_e32 v13, v19
	v_cvt_pk_u8_f32 v18, v13, 3, v12
	v_pk_add_f32 v[12:13], v[114:115], v[44:45]
	v_pk_add_f32 v[22:23], v[116:117], v[46:47]
	v_exp_f32_e32 v12, v12
	v_exp_f32_e32 v13, v13
	v_exp_f32_e32 v19, v22
	v_exp_f32_e32 v22, v23
	v_fmamk_f32 v12, v12, 0x3b808081, v251
	v_rcp_f32_e32 v12, v12
	v_fmamk_f32 v13, v13, 0x3b808081, v251
	v_rcp_f32_e32 v13, v13
	v_fmamk_f32 v19, v19, 0x3b808081, v251
	v_rcp_f32_e32 v19, v19
	v_fmamk_f32 v22, v22, 0x3b808081, v251
	v_rcp_f32_e32 v22, v22
	v_rndne_f32_e32 v12, v12
	v_cvt_pk_u8_f32 v12, v12, 0, 0
	v_rndne_f32_e32 v13, v13
	v_cvt_pk_u8_f32 v12, v13, 1, v12
	v_rndne_f32_e32 v13, v19
	v_cvt_pk_u8_f32 v12, v13, 2, v12
	v_rndne_f32_e32 v13, v22
	v_cvt_pk_u8_f32 v19, v13, 3, v12
	v_permlane16_swap_b32_e32 v16, v18
	s_nop 0
	v_permlane16_swap_b32_e32 v17, v19
	v_lshl_add_u64 v[12:13], v[20:21], 0, v[10:11]
	global_store_dwordx4 v[12:13], v[16:19], off
	v_pk_add_f32 v[12:13], v[110:111], v[40:41]
	v_pk_add_f32 v[6:7], v[102:103], v[40:41]
	v_exp_f32_e32 v12, v12
	v_pk_add_f32 v[16:17], v[112:113], v[42:43]
	v_exp_f32_e32 v13, v13
	v_exp_f32_e32 v16, v16
	v_exp_f32_e32 v17, v17
	v_fmamk_f32 v12, v12, 0x3b808081, v251
	v_rcp_f32_e32 v12, v12
	v_fmamk_f32 v13, v13, 0x3b808081, v251
	v_rcp_f32_e32 v13, v13
	v_fmamk_f32 v16, v16, 0x3b808081, v251
	v_rcp_f32_e32 v16, v16
	v_fmamk_f32 v17, v17, 0x3b808081, v251
	v_rcp_f32_e32 v17, v17
	v_rndne_f32_e32 v12, v12
	v_cvt_pk_u8_f32 v12, v12, 0, 0
	v_rndne_f32_e32 v13, v13
	v_cvt_pk_u8_f32 v12, v13, 1, v12
	v_rndne_f32_e32 v13, v16
	v_cvt_pk_u8_f32 v12, v13, 2, v12
	v_rndne_f32_e32 v13, v17
	v_cvt_pk_u8_f32 v16, v13, 3, v12
	v_pk_add_f32 v[12:13], v[106:107], v[44:45]
	v_pk_add_f32 v[2:3], v[98:99], v[44:45]
	v_exp_f32_e32 v12, v12
	v_exp_f32_e32 v6, v6
	v_exp_f32_e32 v2, v2
	v_pk_add_f32 v[18:19], v[108:109], v[46:47]
	v_exp_f32_e32 v13, v13
	v_pk_add_f32 v[8:9], v[104:105], v[42:43]
	v_exp_f32_e32 v7, v7
	v_pk_add_f32 v[4:5], v[100:101], v[46:47]
	v_exp_f32_e32 v3, v3
	v_exp_f32_e32 v17, v18
	v_exp_f32_e32 v8, v8
	v_exp_f32_e32 v4, v4
	v_exp_f32_e32 v18, v19
	v_exp_f32_e32 v9, v9
	v_exp_f32_e32 v5, v5
	v_fmamk_f32 v12, v12, 0x3b808081, v251
	v_fmamk_f32 v6, v6, 0x3b808081, v251
	v_fmamk_f32 v2, v2, 0x3b808081, v251
	v_rcp_f32_e32 v12, v12
	v_fmamk_f32 v13, v13, 0x3b808081, v251
	v_rcp_f32_e32 v6, v6
	v_fmamk_f32 v7, v7, 0x3b808081, v251
	v_rcp_f32_e32 v2, v2
	v_fmamk_f32 v3, v3, 0x3b808081, v251
	v_rcp_f32_e32 v13, v13
	v_fmamk_f32 v17, v17, 0x3b808081, v251
	v_rcp_f32_e32 v7, v7
	v_fmamk_f32 v8, v8, 0x3b808081, v251
	v_rcp_f32_e32 v3, v3
	v_fmamk_f32 v4, v4, 0x3b808081, v251
	v_rcp_f32_e32 v17, v17
	v_fmamk_f32 v18, v18, 0x3b808081, v251
	v_rcp_f32_e32 v8, v8
	v_fmamk_f32 v9, v9, 0x3b808081, v251
	v_rcp_f32_e32 v4, v4
	v_fmamk_f32 v5, v5, 0x3b808081, v251
	v_rcp_f32_e32 v18, v18
	v_rcp_f32_e32 v9, v9
	v_rcp_f32_e32 v5, v5
	v_rndne_f32_e32 v12, v12
	v_rndne_f32_e32 v6, v6
	v_rndne_f32_e32 v2, v2
	v_cvt_pk_u8_f32 v12, v12, 0, 0
	v_rndne_f32_e32 v13, v13
	v_cvt_pk_u8_f32 v6, v6, 0, 0
	v_rndne_f32_e32 v7, v7
	v_cvt_pk_u8_f32 v2, v2, 0, 0
	v_rndne_f32_e32 v3, v3
	v_cvt_pk_u8_f32 v12, v13, 1, v12
	v_rndne_f32_e32 v13, v17
	v_cvt_pk_u8_f32 v6, v7, 1, v6
	v_rndne_f32_e32 v7, v8
	v_cvt_pk_u8_f32 v2, v3, 1, v2
	v_rndne_f32_e32 v3, v4
	v_cvt_pk_u8_f32 v12, v13, 2, v12
	v_rndne_f32_e32 v13, v18
	v_cvt_pk_u8_f32 v6, v7, 2, v6
	v_rndne_f32_e32 v7, v9
	v_cvt_pk_u8_f32 v2, v3, 2, v2
	v_rndne_f32_e32 v3, v5
	v_cvt_pk_u8_f32 v17, v13, 3, v12
	v_cvt_pk_u8_f32 v18, v7, 3, v6
	v_cvt_pk_u8_f32 v19, v3, 3, v2
	s_nop 0
	v_permlane16_swap_b32_e32 v16, v18
	v_permlane16_swap_b32_e32 v17, v19
	v_lshl_add_u64 v[2:3], v[14:15], 0, v[10:11]
	global_store_dwordx4 v[2:3], v[16:19], off
	s_cbranch_vccnz .LBB0_263
	s_andn2_b64 vcc, exec, s[8:9]
	s_cbranch_vccnz .LBB0_262
	s_barrier
	s_branch .LBB0_262
